# PV blocks: counted lgkmcnt waits at each MFMA instead of full drains (on top of 4-bit K swizzle)
# speedup vs baseline: 1.0056x; 1.0056x over previous
; #define SBAR() __builtin_amdgcn_sched_barrier(0)
; template <int OFF> DEVFI s16x4 tr_read(int vb) { s16x4 r; asm volatile("ds_read_b64_tr_b16 %0, %1 offset:%2" : "=&v"(r) : "v"(vb), "i"(OFF) : "memory"); return r; }
; DEVFI void partialSM2(f32x16& p0, f32x16& p1, float& mhat, f32x16& negm, float& alpha, const float thr2, const bool first) {
;     float pmax = p0[0];
; #pragma unroll
;     for (int r = 1; r < 16; ++r) pmax = fmaxf(pmax, p0[r]);
; #pragma unroll
;     for (int r = 0; r < 16; ++r) pmax = fmaxf(pmax, p1[r]);
;     { auto rr = __builtin_amdgcn_permlane32_swap(__float_as_uint(pmax), __float_as_uint(pmax), false, false);
;       pmax = fmaxf(__uint_as_float(rr[0]), __uint_as_float(rr[1])); }
;     alpha = 1.f;
;     if (first || !__all(pmax <= thr2)) {
;         const float dl = first ? pmax : fmaxf(pmax, 0.f);
;         mhat += dl; alpha = first ? 1.f : __builtin_amdgcn_exp2f(-dl);
; #pragma unroll
;         for (int r = 0; r < 16; ++r) { p0[r] -= dl; p1[r] -= dl; }
; #pragma unroll
;         for (int r = 0; r < 16; ++r) negm[r] = -mhat;
;         asm volatile("" : "+v"(negm));
;     }
; template <int NCB, int D0> DEVFI void pv_one(f32x16& od, int vb, bf16x8 pa0, bf16x8 pa1, bf16x8 pa2, bf16x8 pa3) {
;     ...
;     const s16x4 l0 = tr_read<VOFF(0, 0)>(vb), h0 = tr_read<VOFF(0, 1)>(vb), l1 = tr_read<VOFF(1, 0)>(vb), h1 = tr_read<VOFF(1, 1)>(vb);
;     const s16x4 l2 = tr_read<VOFF(2, 0)>(vb), h2 = tr_read<VOFF(2, 1)>(vb), l3 = tr_read<VOFF(3, 0)>(vb), h3 = tr_read<VOFF(3, 1)>(vb);
;     ...
;     asm volatile("s_waitcnt lgkmcnt(0)" ::: "memory"); SBAR();
;     ...
;     od = __builtin_amdgcn_mfma_f32_32x32x16_bf16(pa0, PK(l0, h0), od, 0, 0, 0);
;     od = __builtin_amdgcn_mfma_f32_32x32x16_bf16(pa1, PK(l1, h1), od, 0, 0, 0);
;     od = __builtin_amdgcn_mfma_f32_32x32x16_bf16(pa2, PK(l2, h2), od, 0, 0, 0);
;     od = __builtin_amdgcn_mfma_f32_32x32x16_bf16(pa3, PK(l3, h3), od, 0, 0, 0);
;     ...
; }
.LBB0_1153:
	s_or_b64 exec, exec, s[0:1]
	v_lshl_add_u64 v[162:163], s[10:11], 0, v[156:157]
	v_add_co_u32_e32 v4, vcc, 0x2fc30000, v162
	s_nop 1
	v_addc_co_u32_e32 v5, vcc, 0, v163, vcc
	global_load_dwordx4 v[4:7], v[4:5], off
	ds_read_b64_tr_b16 v[74:75], v171 offset:0
	ds_read_b64_tr_b16 v[76:77], v171 offset:0x400
	ds_read_b64_tr_b16 v[182:183], v171 offset:0x800
	ds_read_b64_tr_b16 v[184:185], v171 offset:0xc00
	ds_read_b64_tr_b16 v[186:187], v171 offset:0x1000
	ds_read_b64_tr_b16 v[188:189], v171 offset:0x1400
	ds_read_b64_tr_b16 v[202:203], v171 offset:0x1800
	ds_read_b64_tr_b16 v[204:205], v171 offset:0x1c00
	s_waitcnt lgkmcnt(6)
	s_nop 0
	v_mfma_f32_32x32x16_bf16 v[30:45], v[8:11], v[74:77], v[30:45]
	ds_read_b64_tr_b16 v[74:75], v171 offset:0x200
	ds_read_b64_tr_b16 v[76:77], v171 offset:0x600
	s_waitcnt lgkmcnt(6)
	v_mfma_f32_32x32x16_bf16 v[30:45], v[62:65], v[182:185], v[30:45]
	ds_read_b64_tr_b16 v[182:183], v171 offset:0xa00
	ds_read_b64_tr_b16 v[184:185], v171 offset:0xe00
	s_waitcnt lgkmcnt(6)
	v_mfma_f32_32x32x16_bf16 v[30:45], v[66:69], v[186:189], v[30:45]
	ds_read_b64_tr_b16 v[186:187], v171 offset:0x1200
	ds_read_b64_tr_b16 v[188:189], v171 offset:0x1600
	s_waitcnt lgkmcnt(6)
	v_mfma_f32_32x32x16_bf16 v[30:45], v[70:73], v[202:205], v[30:45]
	ds_read_b64_tr_b16 v[202:203], v171 offset:0x1a00
	ds_read_b64_tr_b16 v[204:205], v171 offset:0x1e00
	s_waitcnt lgkmcnt(6)
	v_mfma_f32_32x32x16_bf16 v[14:29], v[8:11], v[74:77], v[14:29]
	v_max_f32_e32 v8, v95, v95
	v_max_f32_e32 v9, v94, v94
	v_max_f32_e32 v8, v9, v8
	v_max3_f32 v8, v8, v96, v97
	v_max3_f32 v8, v8, v98, v99
	v_max3_f32 v8, v8, v100, v101
	v_max3_f32 v8, v8, v102, v103
	s_waitcnt lgkmcnt(4)
	v_mfma_f32_32x32x16_bf16 v[14:29], v[62:65], v[182:185], v[14:29]
	v_max3_f32 v8, v8, v104, v105
	v_max3_f32 v8, v8, v106, v107
	v_max3_f32 v8, v8, v108, v109
	v_max3_f32 v8, v8, v78, v79
	v_max3_f32 v8, v8, v80, v81
	v_max3_f32 v8, v8, v82, v83
	v_max3_f32 v8, v8, v84, v85
	s_waitcnt lgkmcnt(2)
	v_mfma_f32_32x32x16_bf16 v[14:29], v[66:69], v[186:189], v[14:29]
	v_max3_f32 v8, v8, v86, v87
	v_max3_f32 v8, v8, v88, v89
	v_max3_f32 v8, v8, v90, v91
	v_max3_f32 v8, v8, v92, v93
	v_mov_b32_e32 v9, v8
	s_nop 1
	v_permlane32_swap_b32_e32 v8, v9
	s_waitcnt lgkmcnt(0)
	v_mfma_f32_32x32x16_bf16 v[14:29], v[70:73], v[202:205], v[14:29]
	v_max_f32_e32 v9, v9, v9
	v_max_f32_e32 v8, v8, v8
	v_max_f32_e32 v8, v8, v9
	v_cmp_ge_f32_e32 vcc, s33, v8
	s_cmp_eq_u64 vcc, exec
	v_mov_b32_e32 v181, 1.0
	s_cbranch_scc1 .LBB0_1155
	v_max_f32_e32 v8, v8, v8
	v_max_f32_e32 v8, 0, v8
	v_exp_f32_e64 v181, -v8
	v_add_f32_e32 v168, v168, v8
	v_xor_b32_e32 v46, 0x80000000, v168
	v_pk_add_f32 v[94:95], v[94:95], v[8:9] op_sel_hi:[1,0] neg_lo:[0,1] neg_hi:[0,1]
	v_pk_add_f32 v[96:97], v[96:97], v[8:9] op_sel_hi:[1,0] neg_lo:[0,1] neg_hi:[0,1]
	v_pk_add_f32 v[98:99], v[98:99], v[8:9] op_sel_hi:[1,0] neg_lo:[0,1] neg_hi:[0,1]
	v_pk_add_f32 v[100:101], v[100:101], v[8:9] op_sel_hi:[1,0] neg_lo:[0,1] neg_hi:[0,1]
	v_pk_add_f32 v[102:103], v[102:103], v[8:9] op_sel_hi:[1,0] neg_lo:[0,1] neg_hi:[0,1]
	v_pk_add_f32 v[104:105], v[104:105], v[8:9] op_sel_hi:[1,0] neg_lo:[0,1] neg_hi:[0,1]
	v_pk_add_f32 v[106:107], v[106:107], v[8:9] op_sel_hi:[1,0] neg_lo:[0,1] neg_hi:[0,1]
	v_pk_add_f32 v[108:109], v[108:109], v[8:9] op_sel_hi:[1,0] neg_lo:[0,1] neg_hi:[0,1]
	v_sub_f32_e32 v93, v93, v8
	v_sub_f32_e32 v92, v92, v8
	v_sub_f32_e32 v91, v91, v8
	v_sub_f32_e32 v90, v90, v8
	v_sub_f32_e32 v89, v89, v8
	v_sub_f32_e32 v88, v88, v8
	v_sub_f32_e32 v87, v87, v8
	v_sub_f32_e32 v86, v86, v8
	v_sub_f32_e32 v85, v85, v8
	v_sub_f32_e32 v84, v84, v8
	v_sub_f32_e32 v83, v83, v8
	v_sub_f32_e32 v82, v82, v8
	v_sub_f32_e32 v81, v81, v8
	v_sub_f32_e32 v80, v80, v8
	v_sub_f32_e32 v79, v79, v8
	v_sub_f32_e32 v78, v78, v8
	v_mov_b32_e32 v47, v46
	v_mov_b32_e32 v48, v46
	v_mov_b32_e32 v49, v46
	v_mov_b32_e32 v50, v46
	v_mov_b32_e32 v51, v46
	v_mov_b32_e32 v52, v46
	v_mov_b32_e32 v53, v46
	v_mov_b32_e32 v54, v46
	v_mov_b32_e32 v55, v46
	v_mov_b32_e32 v56, v46
	v_mov_b32_e32 v57, v46
	v_mov_b32_e32 v58, v46
	v_mov_b32_e32 v59, v46
	v_mov_b32_e32 v60, v46
	v_mov_b32_e32 v61, v46

; #define SBAR() __builtin_amdgcn_sched_barrier(0)
; template <int OFF> DEVFI s16x4 tr_read(int vb) { s16x4 r; asm volatile("ds_read_b64_tr_b16 %0, %1 offset:%2" : "=&v"(r) : "v"(vb), "i"(OFF) : "memory"); return r; }
; DEVFI void partialSM2(f32x16& p0, f32x16& p1, float& mhat, f32x16& negm, float& alpha, const float thr2, const bool first) {
;     float pmax = p0[0];
; #pragma unroll
;     for (int r = 1; r < 16; ++r) pmax = fmaxf(pmax, p0[r]);
; #pragma unroll
;     for (int r = 0; r < 16; ++r) pmax = fmaxf(pmax, p1[r]);
;     { auto rr = __builtin_amdgcn_permlane32_swap(__float_as_uint(pmax), __float_as_uint(pmax), false, false);
;       pmax = fmaxf(__uint_as_float(rr[0]), __uint_as_float(rr[1])); }
;     alpha = 1.f;
;     if (first || !__all(pmax <= thr2)) {
;         const float dl = first ? pmax : fmaxf(pmax, 0.f);
;         mhat += dl; alpha = first ? 1.f : __builtin_amdgcn_exp2f(-dl);
; #pragma unroll
;         for (int r = 0; r < 16; ++r) { p0[r] -= dl; p1[r] -= dl; }
; #pragma unroll
;         for (int r = 0; r < 16; ++r) negm[r] = -mhat;
;         asm volatile("" : "+v"(negm));
;     }
; template <int NCB, int D0> DEVFI void pv_one(f32x16& od, int vb, bf16x8 pa0, bf16x8 pa1, bf16x8 pa2, bf16x8 pa3) {
;     ...
;     const s16x4 l0 = tr_read<VOFF(0, 0)>(vb), h0 = tr_read<VOFF(0, 1)>(vb), l1 = tr_read<VOFF(1, 0)>(vb), h1 = tr_read<VOFF(1, 1)>(vb);
;     const s16x4 l2 = tr_read<VOFF(2, 0)>(vb), h2 = tr_read<VOFF(2, 1)>(vb), l3 = tr_read<VOFF(3, 0)>(vb), h3 = tr_read<VOFF(3, 1)>(vb);
;     ...
;     asm volatile("s_waitcnt lgkmcnt(0)" ::: "memory"); SBAR();
;     ...
;     od = __builtin_amdgcn_mfma_f32_32x32x16_bf16(pa0, PK(l0, h0), od, 0, 0, 0);
;     od = __builtin_amdgcn_mfma_f32_32x32x16_bf16(pa1, PK(l1, h1), od, 0, 0, 0);
;     od = __builtin_amdgcn_mfma_f32_32x32x16_bf16(pa2, PK(l2, h2), od, 0, 0, 0);
;     od = __builtin_amdgcn_mfma_f32_32x32x16_bf16(pa3, PK(l3, h3), od, 0, 0, 0);
;     ...
; }
.LBB0_1165:
	ds_read_b64_tr_b16 v[160:161], v167 offset:0
	ds_read_b64_tr_b16 v[162:163], v167 offset:0x400
	ds_read_b64_tr_b16 v[182:183], v167 offset:0x800
	ds_read_b64_tr_b16 v[184:185], v167 offset:0xc00
	ds_read_b64_tr_b16 v[186:187], v167 offset:0x1000
	ds_read_b64_tr_b16 v[188:189], v167 offset:0x1400
	ds_read_b64_tr_b16 v[202:203], v167 offset:0x1800
	ds_read_b64_tr_b16 v[204:205], v167 offset:0x1c00
	s_waitcnt lgkmcnt(6)
	s_nop 0
	v_mfma_f32_32x32x16_bf16 v[30:45], v[8:11], v[160:163], v[30:45]
	ds_read_b64_tr_b16 v[160:161], v167 offset:0x200
	ds_read_b64_tr_b16 v[162:163], v167 offset:0x600
	s_waitcnt lgkmcnt(6)
	v_mfma_f32_32x32x16_bf16 v[30:45], v[78:81], v[182:185], v[30:45]
	ds_read_b64_tr_b16 v[182:183], v167 offset:0xa00
	ds_read_b64_tr_b16 v[184:185], v167 offset:0xe00
	s_waitcnt lgkmcnt(6)
	v_mfma_f32_32x32x16_bf16 v[30:45], v[82:85], v[186:189], v[30:45]
	ds_read_b64_tr_b16 v[186:187], v167 offset:0x1200
	ds_read_b64_tr_b16 v[188:189], v167 offset:0x1600
	s_waitcnt lgkmcnt(6)
	v_mfma_f32_32x32x16_bf16 v[30:45], v[86:89], v[202:205], v[30:45]
	ds_read_b64_tr_b16 v[202:203], v167 offset:0x1a00
	ds_read_b64_tr_b16 v[204:205], v167 offset:0x1e00
	s_waitcnt lgkmcnt(6)
	v_mfma_f32_32x32x16_bf16 v[14:29], v[8:11], v[160:163], v[14:29]
	v_max_f32_e32 v8, v95, v95
	v_max_f32_e32 v9, v94, v94
	v_max_f32_e32 v8, v9, v8
	v_max3_f32 v8, v8, v96, v97
	v_max3_f32 v8, v8, v98, v99
	v_max3_f32 v8, v8, v100, v101
	v_max3_f32 v8, v8, v102, v103
	s_waitcnt lgkmcnt(4)
	v_mfma_f32_32x32x16_bf16 v[14:29], v[78:81], v[182:185], v[14:29]
	v_max3_f32 v8, v8, v104, v105
	v_max3_f32 v8, v8, v106, v107
	v_max3_f32 v8, v8, v108, v109
	v_max3_f32 v8, v8, v62, v63
	v_max3_f32 v8, v8, v64, v65
	v_max3_f32 v8, v8, v66, v67
	v_max3_f32 v8, v8, v68, v69
	s_waitcnt lgkmcnt(2)
	v_mfma_f32_32x32x16_bf16 v[14:29], v[82:85], v[186:189], v[14:29]
	v_max3_f32 v8, v8, v70, v71
	v_max3_f32 v8, v8, v72, v73
	v_max3_f32 v8, v8, v74, v75
	v_max3_f32 v8, v8, v76, v77
	v_mov_b32_e32 v9, v8
	s_nop 1
	v_permlane32_swap_b32_e32 v8, v9
	s_waitcnt lgkmcnt(0)
	v_mfma_f32_32x32x16_bf16 v[14:29], v[86:89], v[202:205], v[14:29]
	v_max_f32_e32 v9, v9, v9
	v_max_f32_e32 v8, v8, v8
	v_max_f32_e32 v9, v8, v9
	v_cmp_ge_f32_e32 vcc, s33, v9
	s_cmp_eq_u64 vcc, exec
	v_mov_b32_e32 v8, 1.0
	s_cbranch_scc1 .LBB0_1167
	v_max_f32_e32 v8, v9, v9
	v_max_f32_e32 v10, 0, v8
	v_exp_f32_e64 v8, -v10
	v_add_f32_e32 v168, v168, v10
	v_xor_b32_e32 v46, 0x80000000, v168
	v_pk_add_f32 v[94:95], v[94:95], v[10:11] op_sel_hi:[1,0] neg_lo:[0,1] neg_hi:[0,1]
	v_pk_add_f32 v[96:97], v[96:97], v[10:11] op_sel_hi:[1,0] neg_lo:[0,1] neg_hi:[0,1]
	v_pk_add_f32 v[98:99], v[98:99], v[10:11] op_sel_hi:[1,0] neg_lo:[0,1] neg_hi:[0,1]
	v_pk_add_f32 v[100:101], v[100:101], v[10:11] op_sel_hi:[1,0] neg_lo:[0,1] neg_hi:[0,1]
	v_pk_add_f32 v[102:103], v[102:103], v[10:11] op_sel_hi:[1,0] neg_lo:[0,1] neg_hi:[0,1]
	v_pk_add_f32 v[104:105], v[104:105], v[10:11] op_sel_hi:[1,0] neg_lo:[0,1] neg_hi:[0,1]
	v_pk_add_f32 v[106:107], v[106:107], v[10:11] op_sel_hi:[1,0] neg_lo:[0,1] neg_hi:[0,1]
	v_pk_add_f32 v[108:109], v[108:109], v[10:11] op_sel_hi:[1,0] neg_lo:[0,1] neg_hi:[0,1]
	v_sub_f32_e32 v77, v77, v10
	v_sub_f32_e32 v76, v76, v10
	v_sub_f32_e32 v75, v75, v10
	v_sub_f32_e32 v74, v74, v10
	v_sub_f32_e32 v73, v73, v10
	v_sub_f32_e32 v72, v72, v10
	v_sub_f32_e32 v71, v71, v10
	v_sub_f32_e32 v70, v70, v10
	v_sub_f32_e32 v69, v69, v10
	v_sub_f32_e32 v68, v68, v10
	v_sub_f32_e32 v67, v67, v10
	v_sub_f32_e32 v66, v66, v10
	v_sub_f32_e32 v65, v65, v10
	v_sub_f32_e32 v64, v64, v10
	v_sub_f32_e32 v63, v63, v10
	v_sub_f32_e32 v62, v62, v10
	v_mov_b32_e32 v47, v46
	v_mov_b32_e32 v48, v46
	v_mov_b32_e32 v49, v46
	v_mov_b32_e32 v50, v46
	v_mov_b32_e32 v51, v46
	v_mov_b32_e32 v52, v46
	v_mov_b32_e32 v53, v46
	v_mov_b32_e32 v54, v46
	v_mov_b32_e32 v55, v46
	v_mov_b32_e32 v56, v46
	v_mov_b32_e32 v57, v46
	v_mov_b32_e32 v58, v46
	v_mov_b32_e32 v59, v46
	v_mov_b32_e32 v60, v46
	v_mov_b32_e32 v61, v46
